# strategy: pair narrow stores into wide ones -- scan step computes out and the state update transposed (MFMA A/B swapped) so the 4 global_store_short become one global_store_dwordx2 and 8 ds_write_b16
# speedup vs baseline: 1.0104x; 1.0036x over previous
; #define LAS __attribute__((address_space(3)))
; __device__ __forceinline__ void phase_gdn_scan(const int wid_s, CParams& p, LAS unsigned char* lds) {
;     ...
;     for (int chain = blockIdx.x; chain < 256; chain += gridDim.x) {
;         const int b = chain >> 4, h = (chain >> 2) & 3, sl = chain & 3;
;         for (int i = tid; i < 32 * 136; i += NTHREADS) St[i] = (h16)0.f;
;         f32x4 st[2] = {{0.f, 0.f, 0.f, 0.f}, {0.f, 0.f, 0.f, 0.f}};
;         const int vt = wave & 1, wq = wave >> 1;
;         __syncthreads();
;         int cur = 0;
;         h16x8 wf[4], qf[4], inf[2], kf[2][2]; h16x4 uu; float egl;
;         h16x8 wfn[4], qfn[4], infn[2], kfn[2][2]; h16x4 uun; float egln;
;     ...
;         SCAN_LOAD(wf, uu, qf, inf, kf, egl, 0);
;         for (int n = 0; n < 64; ++n) {
;             const int tc0 = b * SEQ + n * 64;
;             const LAS h16* Sc = St + cur * (32 * 136); LAS h16* Sn = St + (cur ^ 1) * (32 * 136);
;             { const int nn = n + 1 < 64 ? n + 1 : n; SCAN_LOAD(wfn, uun, qfn, infn, kfn, egln, nn); }
.LBB0_1284:
	s_or_b64 exec, exec, s[10:11]
	s_lshl_b32 s10, s18, 8
	s_and_b32 s10, s10, 0xfffff000
	v_add_u32_e32 v2, s10, v116
	v_mov_b64_e32 v[4:5], s[4:5]
	s_bfe_u32 s7, s18, 0x20002
	v_ashrrev_i32_e32 v3, 31, v2
	v_mad_i64_i32 v[4:5], s[12:13], v2, s86, v[4:5]
	s_ashr_i32 s11, s10, 4
	s_lshl_b32 s58, s7, 8
	s_lshl_b32 s12, s18, 6
	v_lshlrev_b64 v[2:3], 10, v[2:3]
	v_lshl_add_u64 v[4:5], v[4:5], 0, s[58:59]
	s_and_b32 s12, s12, 0xc0
	s_mov_b32 s13, s59
	v_lshl_add_u64 v[2:3], s[8:9], 0, v[2:3]
	s_or_b32 s20, s11, s7
	v_lshl_add_u64 v[10:11], v[4:5], 0, v[0:1]
	v_lshl_add_u64 v[4:5], v[4:5], 0, s[12:13]
	v_mov_b32_e32 v135, v1
	v_lshl_add_u64 v[2:3], v[2:3], 0, s[58:59]
	s_ashr_i32 s21, s20, 31
	v_lshl_add_u64 v[4:5], v[4:5], 0, v[134:135]
	v_mov_b32_e32 v137, v1
	v_lshl_add_u64 v[2:3], v[2:3], 0, v[0:1]
	s_lshl_b64 s[22:23], s[20:21], 13
	s_waitcnt lgkmcnt(0)
	s_barrier
	global_load_dwordx4 v[90:93], v[10:11], off offset:64
	global_load_dwordx4 v[98:101], v[10:11], off offset:128
	v_lshl_add_u64 v[4:5], v[4:5], 0, v[136:137]
	global_load_dwordx4 v[38:41], v[10:11], off offset:192
	global_load_dwordx2 v[140:141], v[4:5], off offset:1024
	global_load_dwordx4 v[94:97], v[2:3], off
	global_load_dwordx4 v[102:105], v[2:3], off offset:64
	global_load_dwordx4 v[106:109], v[2:3], off offset:128
	global_load_dwordx4 v[30:33], v[2:3], off offset:192
	v_lshl_add_u64 v[2:3], v[130:131], 0, s[22:23]
	s_lshl_b64 s[22:23], s[20:21], 7
	global_load_dwordx4 v[34:37], v[2:3], off
	global_load_dwordx4 v[26:29], v[2:3], off offset:64
	v_mov_b32_e32 v3, s23
	v_or_b32_e32 v2, s22, v114
	v_lshl_add_u64 v[4:5], v[2:3], 0, v[120:121]
	v_lshl_add_u64 v[2:3], v[2:3], 0, v[132:133]
	s_and_b32 s6, s17, 0xfffff000
	v_lshlrev_b64 v[4:5], 7, v[4:5]
	v_lshlrev_b64 v[2:3], 7, v[2:3]
	s_lshl_b64 s[20:21], s[20:21], 2
	v_lshl_add_u64 v[4:5], v[122:123], 0, v[4:5]
	v_lshl_add_u64 v[2:3], v[122:123], 0, v[2:3]
	s_add_u32 s20, s15, s20
	global_load_dwordx4 v[18:21], v[4:5], off
	global_load_dwordx4 v[14:17], v[4:5], off offset:64
	global_load_dwordx4 v[6:9], v[2:3], off
	s_nop 0
	global_load_dwordx4 v[2:5], v[2:3], off offset:64
	s_addc_u32 s21, s16, s21
	global_load_dwordx4 v[110:113], v[10:11], off
	global_load_dword v154, v1, s[20:21]
	v_lshl_add_u64 v[10:11], v[128:129], 0, s[58:59]
	s_add_u32 s11, s4, s58
	v_lshl_add_u64 v[10:11], v[10:11], 0, s[12:13]
	s_addc_u32 s13, s5, 0
	s_add_u32 s12, s11, s12
	s_addc_u32 s13, s13, 0
	v_lshl_add_u64 v[138:139], v[10:11], 0, v[134:135]
	v_lshl_add_u64 v[10:11], s[12:13], 0, v[134:135]
	v_lshl_add_u64 v[146:147], v[10:11], 0, v[136:137]
	v_mov_b32_e32 v10, 0
	v_add_u32_e32 v155, s6, v119
	v_mbcnt_lo_u32_b32 v177, -1, 0
	v_mbcnt_hi_u32_b32 v177, -1, v177
	v_and_b32_e32 v176, 15, v177
	v_lshrrev_b32_e32 v177, 4, v177
	v_lshlrev_b32_e32 v180, 2, v177
	v_sub_u32_e32 v180, v176, v180
	v_lshlrev_b32_e32 v177, 3, v177
	v_lshlrev_b32_e32 v176, 1, v176
	v_sub_u32_e32 v178, v177, v176
	v_ashrrev_i32_e32 v179, 31, v178
	v_lshl_add_u64 v[178:179], v[138:139], 0, v[178:179]
	v_add_u32_e32 v176, v155, v180
	v_mul_i32_i24_e32 v182, 0x10e, v180
	v_add_u32_e32 v161, s6, v152
	v_lshl_add_u64 v[142:143], v[124:125], 0, s[58:59]
	v_lshl_add_u64 v[144:145], v[126:127], 0, s[58:59]
	s_mov_b32 s12, 0
	s_mov_b32 s11, 0
	v_mov_b32_e32 v11, v10
	v_mov_b32_e32 v12, v10
	v_mov_b32_e32 v13, v10
	v_mov_b32_e32 v22, v10
	v_mov_b32_e32 v23, v10
	v_mov_b32_e32 v24, v10
	v_mov_b32_e32 v25, v10
	s_waitcnt vmcnt(0)
.LBB0_1285:
	v_mov_b64_e32 v[68:69], v[4:5]
	v_mov_b64_e32 v[66:67], v[2:3]
	s_add_i32 s13, s12, 64
	v_add_u32_e32 v2, s12, v161
	v_mov_b64_e32 v[168:169], v[40:41]
	s_add_i32 s19, s13, s6
	v_mad_i64_i32 v[4:5], s[20:21], v2, s86, v[142:143]
	v_mov_b64_e32 v[166:167], v[38:39]
	s_ashr_i32 s22, s19, 4
	global_load_dwordx4 v[62:65], v[4:5], off
	global_load_dwordx4 v[58:61], v[4:5], off offset:64
	global_load_dwordx4 v[54:57], v[4:5], off offset:128
	global_load_dwordx4 v[38:41], v[4:5], off offset:192
	v_mad_i64_i32 v[4:5], s[20:21], v2, s86, v[146:147]
	v_ashrrev_i32_e32 v3, 31, v2
	s_or_b32 s20, s22, s7
	v_lshlrev_b64 v[2:3], 10, v[2:3]
	s_ashr_i32 s21, s20, 31
	v_mov_b64_e32 v[164:165], v[32:33]
	v_lshl_add_u64 v[2:3], v[144:145], 0, v[2:3]
	s_lshl_b64 s[22:23], s[20:21], 13
	v_mov_b64_e32 v[162:163], v[30:31]
	v_mov_b64_e32 v[174:175], v[140:141]
	v_mov_b64_e32 v[88:89], v[36:37]
	v_mov_b64_e32 v[84:85], v[28:29]
	global_load_dwordx2 v[140:141], v[4:5], off offset:1024
	global_load_dwordx4 v[50:53], v[2:3], off
	global_load_dwordx4 v[46:49], v[2:3], off offset:64
	global_load_dwordx4 v[42:45], v[2:3], off offset:128
	global_load_dwordx4 v[30:33], v[2:3], off offset:192
	v_lshl_add_u64 v[2:3], v[130:131], 0, s[22:23]
	s_lshl_b64 s[22:23], s[20:21], 7
	v_mov_b64_e32 v[86:87], v[34:35]
	v_mov_b64_e32 v[82:83], v[26:27]
	global_load_dwordx4 v[34:37], v[2:3], off
	global_load_dwordx4 v[26:29], v[2:3], off offset:64
	v_mov_b32_e32 v3, s23
	v_or_b32_e32 v2, s22, v114
	v_lshl_add_u64 v[4:5], v[2:3], 0, v[120:121]
	v_lshl_add_u64 v[2:3], v[2:3], 0, v[132:133]
	s_mul_i32 s24, s11, 0x2200
	v_lshlrev_b64 v[4:5], 7, v[4:5]
	v_lshlrev_b64 v[2:3], 7, v[2:3]
	v_mov_b64_e32 v[80:81], v[20:21]
	v_mov_b64_e32 v[76:77], v[16:17]
	v_mov_b64_e32 v[72:73], v[8:9]
	v_lshl_add_u64 v[4:5], v[122:123], 0, v[4:5]
	v_lshl_add_u64 v[2:3], v[122:123], 0, v[2:3]
	v_add_u32_e32 v135, s24, v117
	v_mov_b64_e32 v[78:79], v[18:19]
	v_mov_b64_e32 v[74:75], v[14:15]
	v_mov_b64_e32 v[70:71], v[6:7]
	global_load_dwordx4 v[18:21], v[4:5], off
	global_load_dwordx4 v[14:17], v[4:5], off offset:64
	global_load_dwordx4 v[6:9], v[2:3], off
	s_nop 0
	global_load_dwordx4 v[2:5], v[2:3], off offset:64
	ds_read_b128 v[200:203], v135
	ds_read_b128 v[204:207], v135 offset:64
	ds_read_b128 v[208:211], v135 offset:128
	ds_read_b128 v[212:215], v135 offset:192
	s_xor_b32 s11, s11, 1
	s_lshl_b64 s[20:21], s[20:21], 2
	s_add_u32 s20, s15, s20
	s_addc_u32 s21, s16, s21
	v_mov_b32_e32 v137, v154
	global_load_dword v154, v1, s[20:21]
	s_waitcnt lgkmcnt(3)
; #define LAS __attribute__((address_space(3)))
; __device__ __forceinline__ f32x4 mma16(const h16x8 a, const h16x8 b, const f32x4 c) { return __builtin_amdgcn_mfma_f32_16x16x32_f16(a, b, c, 0, 0, 0); }
; __device__ __forceinline__ void phase_gdn_scan(const int wid_s, CParams& p, LAS unsigned char* lds) {
;     ...
;             {
;                 f32x4 acc = {0.f, 0.f, 0.f, 0.f};
; #pragma unroll
;                 for (int ks = 0; ks < 4; ++ks) acc = mma16(*(const LAS h16x8*)(Sc + (16 * vt + lr) * 136 + 32 * ks + 8 * lq), wf[ks], acc);
; #pragma unroll
;                 for (int r = 0; r < 4; ++r) Vnt[(16 * vt + 4 * lq + r) * 72 + 16 * wq + lr] = (h16)((float)uu[r] - acc[r]);
;             }
;             __syncthreads();
;             {
;                 f32x4 acc = {0.f, 0.f, 0.f, 0.f};
; #pragma unroll
;                 for (int ks = 0; ks < 4; ++ks) acc = mma16(qf[ks], *(const LAS h16x8*)(Sc + (16 * vt + lr) * 136 + 32 * ks + 8 * lq), acc);
; #pragma unroll
;                 for (int ks = 0; ks < 2; ++ks) acc = mma16(inf[ks], *(const LAS h16x8*)(Vnt + (16 * vt + lr) * 72 + 32 * ks + 8 * lq), acc);
; #pragma unroll
;                 for (int r = 0; r < 4; ++r) y[(size_t)(tc0 + 16 * wq + 4 * lq + r) * D + 512 + h * 128 + 32 * sl + 16 * vt + lr] = (h16)acc[r];
;             }
; #pragma unroll
;             for (int i = 0; i < 2; ++i) {
;                 f32x4 acc = st[i] * __expf(egl);
; #pragma unroll
;                 for (int ks = 0; ks < 2; ++ks) acc = mma16(*(const LAS h16x8*)(Vnt + (16 * vt + lr) * 72 + 32 * ks + 8 * lq), kf[i][ks], acc);
;                 st[i] = acc;
; #pragma unroll
;                 for (int r = 0; r < 4; ++r) Sn[(16 * vt + 4 * lq + r) * 136 + 16 * (2 * wq + i) + lr] = (h16)acc[r];
;             }
;             __syncthreads();
;             cur ^= 1;
; #pragma unroll
;             for (int ks = 0; ks < 4; ++ks) { wf[ks] = wfn[ks]; qf[ks] = qfn[ks]; }
; #pragma unroll
;             for (int ks = 0; ks < 2; ++ks) { inf[ks] = infn[ks]; kf[0][ks] = kfn[0][ks]; kf[1][ks] = kfn[1][ks]; }
;             uu = uun; egl = egln;
	v_mfma_f32_16x16x32_f16 v[110:113], v[200:203], v[110:113], 0
	s_waitcnt lgkmcnt(2)
	v_mfma_f32_16x16x32_f16 v[90:93], v[204:207], v[90:93], v[110:113]
	s_waitcnt lgkmcnt(1)
	v_mfma_f32_16x16x32_f16 v[90:93], v[208:211], v[98:101], v[90:93]
	s_waitcnt lgkmcnt(0)
	v_mfma_f32_16x16x32_f16 v[90:93], v[212:215], v[166:169], v[90:93]
	v_mfma_f32_16x16x32_f16 v[184:187], v[200:203], v[94:97], 0
	v_mfma_f32_16x16x32_f16 v[184:187], v[204:207], v[102:105], v[184:187]
	v_mfma_f32_16x16x32_f16 v[184:187], v[208:211], v[106:109], v[184:187]
	v_mfma_f32_16x16x32_f16 v[184:187], v[212:215], v[162:165], v[184:187]
	v_cvt_f32_f16_e32 v98, v174
	s_mul_i32 s19, s11, 0x2200
	s_cmpk_eq_i32 s13, 0xfc0
	s_nop 0
	s_nop 0
	s_nop 2
	v_sub_f32_e32 v90, v98, v90
	v_cvt_f16_f32_e32 v90, v90
	s_nop 0
	s_nop 0
	s_nop 0
	ds_write_b16 v153, v90 offset:17408
	v_cvt_f32_f16_sdwa v90, v174 dst_sel:DWORD dst_unused:UNUSED_PAD src0_sel:WORD_1
	s_nop 0
	s_nop 0
	s_nop 0
	s_nop 0
	v_sub_f32_e32 v90, v90, v91
	v_cvt_f16_f32_e32 v90, v90
	s_nop 0
	ds_write_b16 v153, v90 offset:17552
	v_cvt_f32_f16_e32 v90, v175
	v_sub_f32_e32 v90, v90, v92
	v_cvt_f16_f32_e32 v90, v90
	ds_write_b16 v153, v90 offset:17696
	v_cvt_f32_f16_sdwa v90, v175 dst_sel:DWORD dst_unused:UNUSED_PAD src0_sel:WORD_1
	v_sub_f32_e32 v90, v90, v93
	v_cvt_f16_f32_e32 v90, v90
	ds_write_b16 v153, v90 offset:17840
	s_waitcnt lgkmcnt(0)
	s_barrier
	v_add_u32_e32 v135, v115, v118
	ds_read_b128 v[94:97], v135 offset:17408
	ds_read_b128 v[90:93], v135 offset:17472
	s_waitcnt lgkmcnt(1)
	v_mfma_f32_16x16x32_f16 v[86:89], v[94:97], v[86:89], v[184:187]
	s_waitcnt lgkmcnt(0)
	v_mfma_f32_16x16x32_f16 v[82:85], v[90:93], v[82:85], v[86:89]
	s_nop 2
	v_add_u32_e32 v86, s12, v176
	v_ashrrev_i32_e32 v87, 31, v86
	v_lshlrev_b64 v[88:89], 11, v[86:87]
	s_nop 1
	v_lshl_add_u64 v[88:89], v[178:179], 0, v[88:89]
	v_cvt_pk_f16_f32 v82, v82, v83
	v_cvt_pk_f16_f32 v83, v84, v85
	global_store_dwordx2 v[88:89], v[82:83], off
	v_mul_f32_e32 v82, 0x3fb8aa3b, v137
	v_exp_f32_e32 v82, v82
	s_mov_b32 s12, s13
	s_nop 0
	v_pk_mul_f32 v[24:25], v[24:25], v[82:83] op_sel_hi:[1,0]
	v_pk_mul_f32 v[22:23], v[22:23], v[82:83] op_sel_hi:[1,0]
	v_pk_mul_f32 v[12:13], v[12:13], v[82:83] op_sel_hi:[1,0]
	v_pk_mul_f32 v[10:11], v[10:11], v[82:83] op_sel_hi:[1,0]
	v_mfma_f32_16x16x32_f16 v[22:25], v[78:81], v[94:97], v[22:25]
	v_add3_u32 v78, v148, s19, v149
	s_nop 0
	s_nop 0
	v_mfma_f32_16x16x32_f16 v[22:25], v[74:77], v[90:93], v[22:25]
	v_mfma_f32_16x16x32_f16 v[10:13], v[70:73], v[94:97], v[10:13]
	v_mfma_f32_16x16x32_f16 v[10:13], v[66:69], v[90:93], v[10:13]
	s_nop 0
	s_nop 0
	s_nop 0
	s_nop 0
	s_nop 0
	s_nop 2
	v_add_u32_e32 v78, v78, v182
	v_cvt_pk_f16_f32 v74, v22, v23
	v_cvt_pk_f16_f32 v75, v24, v25
	ds_write_b64 v78, v[74:75]
	s_nop 7
	v_cvt_pk_f16_f32 v66, v10, v11
	v_cvt_pk_f16_f32 v67, v12, v13
	ds_write_b64 v78, v[66:67] offset:32
	s_waitcnt vmcnt(1)
	v_mov_b32_e32 v110, v62
	v_mov_b32_e32 v111, v63
	v_mov_b32_e32 v112, v64
	v_mov_b32_e32 v113, v65
	v_mov_b32_e32 v98, v54
	v_mov_b32_e32 v99, v55
	v_mov_b32_e32 v100, v56
	v_mov_b32_e32 v101, v57
	v_mov_b32_e32 v102, v46
	v_mov_b32_e32 v103, v47
	v_mov_b32_e32 v104, v48
	v_mov_b32_e32 v105, v49
	v_mov_b32_e32 v106, v42
	v_mov_b32_e32 v107, v43
	v_mov_b32_e32 v108, v44
	v_mov_b32_e32 v109, v45
	v_mov_b32_e32 v94, v50
	v_mov_b32_e32 v95, v51
	v_mov_b32_e32 v90, v58
	v_mov_b32_e32 v91, v59
	v_mov_b32_e32 v92, v60
	v_mov_b32_e32 v93, v61
	v_mov_b32_e32 v96, v52
	v_mov_b32_e32 v97, v53
	s_waitcnt lgkmcnt(0)
	s_barrier
	s_cbranch_scc0 .LBB0_1285
; #define LAS __attribute__((address_space(3)))
; __device__ __forceinline__ f32x4 mma16(const h16x8 a, const h16x8 b, const f32x4 c) { return __builtin_amdgcn_mfma_f32_16x16x32_f16(a, b, c, 0, 0, 0); }
; __device__ __forceinline__ void phase_gdn_scan(const int wid_s, CParams& p, LAS unsigned char* lds) {
;     ...
;         for (int n = 0; n < 64; ++n) {
;             const int tc0 = b * SEQ + n * 64;
;             const LAS h16* Sc = St + cur * (32 * 136); LAS h16* Sn = St + (cur ^ 1) * (32 * 136);
;             { const int nn = n + 1 < 64 ? n + 1 : n; SCAN_LOAD(wfn, uun, qfn, infn, kfn, egln, nn); }
;             {
;                 f32x4 acc = {0.f, 0.f, 0.f, 0.f};
; #pragma unroll
;                 for (int ks = 0; ks < 4; ++ks) acc = mma16(*(const LAS h16x8*)(Sc + (16 * vt + lr) * 136 + 32 * ks + 8 * lq), wf[ks], acc);
; #pragma unroll
;                 for (int r = 0; r < 4; ++r) Vnt[(16 * vt + 4 * lq + r) * 72 + 16 * wq + lr] = (h16)((float)uu[r] - acc[r]);
;             }
;             __syncthreads();
;             {
;                 f32x4 acc = {0.f, 0.f, 0.f, 0.f};
; #pragma unroll
;                 for (int ks = 0; ks < 4; ++ks) acc = mma16(qf[ks], *(const LAS h16x8*)(Sc + (16 * vt + lr) * 136 + 32 * ks + 8 * lq), acc);
; #pragma unroll
;                 for (int ks = 0; ks < 2; ++ks) acc = mma16(inf[ks], *(const LAS h16x8*)(Vnt + (16 * vt + lr) * 72 + 32 * ks + 8 * lq), acc);
; #pragma unroll
;                 for (int r = 0; r < 4; ++r) y[(size_t)(tc0 + 16 * wq + 4 * lq + r) * D + 512 + h * 128 + 32 * sl + 16 * vt + lr] = (h16)acc[r];
;             }
; #pragma unroll
;             for (int i = 0; i < 2; ++i) {
;                 f32x4 acc = st[i] * __expf(egl);
; #pragma unroll
;                 for (int ks = 0; ks < 2; ++ks) acc = mma16(*(const LAS h16x8*)(Vnt + (16 * vt + lr) * 72 + 32 * ks + 8 * lq), kf[i][ks], acc);
;                 st[i] = acc;
; #pragma unroll
;                 for (int r = 0; r < 4; ++r) Sn[(16 * vt + 4 * lq + r) * 136 + 16 * (2 * wq + i) + lr] = (h16)acc[r];
;             }
;             __syncthreads();
	ds_read_b128 v[66:69], v117 offset:8704
	v_add_u32_e32 v70, s10, v119
	v_readlane_b32 s6, v253, 0
	s_add_i32 s18, s18, s6
	v_readlane_b32 s6, v253, 57
	s_add_i32 s17, s17, s6
	s_cmpk_gt_i32 s18, 0xff
	s_waitcnt lgkmcnt(0)
	v_mfma_f32_16x16x32_f16 v[62:65], v[66:69], v[62:65], 0
	ds_read_b128 v[66:69], v117 offset:8768
	s_waitcnt lgkmcnt(0)
	v_mfma_f32_16x16x32_f16 v[58:61], v[66:69], v[58:61], v[62:65]
	s_nop 4
	ds_read_b128 v[62:65], v117 offset:8832
	s_waitcnt lgkmcnt(0)
	v_mfma_f32_16x16x32_f16 v[54:57], v[62:65], v[54:57], v[58:61]
	s_nop 2
	ds_read_b128 v[58:61], v117 offset:8896
	s_waitcnt lgkmcnt(0)
	v_mfma_f32_16x16x32_f16 v[38:41], v[58:61], v[38:41], v[54:57]
	s_nop 2
	v_cvt_f32_f16_e32 v54, v140
	s_nop 3
	v_sub_f32_e32 v38, v54, v38
	v_cvt_f16_f32_e32 v38, v38
	ds_write_b16 v153, v38 offset:17408
	v_cvt_f32_f16_sdwa v38, v140 dst_sel:DWORD dst_unused:UNUSED_PAD src0_sel:WORD_1
	v_sub_f32_e32 v38, v38, v39
	v_cvt_f16_f32_e32 v38, v38
	ds_write_b16 v153, v38 offset:17552
	v_cvt_f32_f16_e32 v38, v141
	v_sub_f32_e32 v38, v38, v40
	v_cvt_f16_f32_e32 v38, v38
	ds_write_b16 v153, v38 offset:17696
	v_cvt_f32_f16_sdwa v38, v141 dst_sel:DWORD dst_unused:UNUSED_PAD src0_sel:WORD_1
	v_sub_f32_e32 v38, v38, v41
	v_cvt_f16_f32_e32 v38, v38
	ds_write_b16 v153, v38 offset:17840
	s_waitcnt lgkmcnt(0)
	s_barrier
	ds_read_b128 v[38:41], v117 offset:8704
	s_waitcnt lgkmcnt(0)
	v_mfma_f32_16x16x32_f16 v[38:41], v[50:53], v[38:41], 0
	ds_read_b128 v[50:53], v117 offset:8768
	s_waitcnt lgkmcnt(0)
	v_mfma_f32_16x16x32_f16 v[38:41], v[46:49], v[50:53], v[38:41]
	ds_read_b128 v[46:49], v117 offset:8832
	s_waitcnt lgkmcnt(0)
	v_mfma_f32_16x16x32_f16 v[38:41], v[42:45], v[46:49], v[38:41]
	ds_read_b128 v[42:45], v117 offset:8896
	s_waitcnt vmcnt(11) lgkmcnt(0)
	v_mfma_f32_16x16x32_f16 v[30:33], v[30:33], v[42:45], v[38:41]
	s_nop 4
	ds_read_b128 v[38:41], v135 offset:17408
	s_waitcnt vmcnt(10) lgkmcnt(0)
	v_mfma_f32_16x16x32_f16 v[34:37], v[34:37], v[38:41], v[30:33]
	s_nop 2
	ds_read_b128 v[30:33], v135 offset:17472
	s_waitcnt vmcnt(9) lgkmcnt(0)
	v_mfma_f32_16x16x32_f16 v[26:29], v[26:29], v[30:33], v[34:37]
	s_nop 2
	v_add_u32_e32 v34, 0xfc0, v70
	v_ashrrev_i32_e32 v35, 31, v34
	s_nop 2
	v_cvt_f16_f32_e32 v26, v26
	v_lshlrev_b64 v[34:35], 11, v[34:35]
	v_lshl_add_u64 v[34:35], v[138:139], 0, v[34:35]
	v_cvt_f16_f32_e32 v28, v28
	global_store_short v[34:35], v26, off
	v_cvt_f16_f32_e32 v34, v27
	v_add_u32_e32 v26, 0xfc1, v70
	v_ashrrev_i32_e32 v27, 31, v26
	v_lshlrev_b64 v[26:27], 11, v[26:27]
	v_lshl_add_u64 v[26:27], v[138:139], 0, v[26:27]
	global_store_short v[26:27], v34, off
	v_add_u32_e32 v26, 0xfc2, v70
	v_ashrrev_i32_e32 v27, 31, v26
	v_lshlrev_b64 v[26:27], 11, v[26:27]
	v_lshl_add_u64 v[26:27], v[138:139], 0, v[26:27]
	global_store_short v[26:27], v28, off
	v_cvt_f16_f32_e32 v28, v29
	v_add_u32_e32 v26, 0xfc3, v70
	v_ashrrev_i32_e32 v27, 31, v26
	v_lshlrev_b64 v[26:27], 11, v[26:27]
	v_lshl_add_u64 v[26:27], v[138:139], 0, v[26:27]
	global_store_short v[26:27], v28, off
	s_waitcnt vmcnt(8)
	v_mul_f32_e32 v26, 0x3fb8aa3b, v154
	v_exp_f32_e32 v26, v26
	s_nop 0
	v_pk_mul_f32 v[24:25], v[26:27], v[24:25] op_sel_hi:[0,1]
	v_pk_mul_f32 v[22:23], v[26:27], v[22:23] op_sel_hi:[0,1]
	v_pk_mul_f32 v[12:13], v[26:27], v[12:13] op_sel_hi:[0,1]
	v_pk_mul_f32 v[10:11], v[26:27], v[10:11] op_sel_hi:[0,1]
	v_mfma_f32_16x16x32_f16 v[18:21], v[38:41], v[18:21], v[22:25]
	v_mfma_f32_16x16x32_f16 v[14:17], v[30:33], v[14:17], v[18:21]
	s_nop 6
	v_add_u32_e32 v18, v148, v149
	v_cvt_f16_f32_e32 v14, v14
	ds_write_b16 v18, v14
	v_cvt_f16_f32_e32 v14, v15
	ds_write_b16 v18, v14 offset:272
	v_cvt_f16_f32_e32 v14, v16
	ds_write_b16 v18, v14 offset:544
	v_cvt_f16_f32_e32 v14, v17
	ds_write_b16 v18, v14 offset:816
	ds_read_b128 v[14:17], v135 offset:17408
	s_waitcnt lgkmcnt(0)
	v_mfma_f32_16x16x32_f16 v[6:9], v[14:17], v[6:9], v[10:13]
	s_nop 2
	ds_read_b128 v[10:13], v135 offset:17472
	s_waitcnt lgkmcnt(0)
	v_mfma_f32_16x16x32_f16 v[2:5], v[10:13], v[2:5], v[6:9]
	s_nop 7
	v_cvt_f16_f32_e32 v2, v2
	ds_write_b16 v18, v2 offset:32
	v_cvt_f16_f32_e32 v2, v3
	ds_write_b16 v18, v2 offset:304
	v_cvt_f16_f32_e32 v2, v4
	ds_write_b16 v18, v2 offset:576
	v_cvt_f16_f32_e32 v2, v5
	ds_write_b16 v18, v2 offset:848
	s_waitcnt lgkmcnt(0)
	s_barrier
	s_cbranch_scc0 .LBB0_1281
